# G1 grouped half-sweeps: selection for 4 tokens (lists in per-token LDS slots), then u-table batches of one list half for the 4 tokens, then the other half; h2 prefetched a token ahead, row scales fetc
# baseline (speedup 1.0000x reference)
.LBB0_975:
	s_or_b64 exec, exec, s[4:5]
	s_mov_b64 s[4:5], s[0:1]
	v_mov_b32_e32 v1, v176
	s_waitcnt lgkmcnt(0)
	s_barrier
	s_mov_b32 s46, 0x8400
	v_ashrrev_i32_e32 v0, 6, v1
	v_mul_lo_u32 v2, v0, s70
	v_add_u32_e32 v116, s2, v2
	s_lshl_b32 s33, s70, 3
	v_cmp_gt_i32_e32 vcc, s46, v116
	s_and_saveexec_b64 s[30:31], vcc
	s_cbranch_execz .LBB0_1038
	s_load_dwordx2 s[14:15], s[4:5], 0xf8
	v_ashrrev_i32_e32 v117, 31, v116
	v_and_b32_e32 v124, 63, v1
	v_lshlrev_b64 v[4:5], 10, v[116:117]
	v_mov_b32_e32 v3, 0
	s_waitcnt lgkmcnt(0)
	s_add_u32 s16, s14, 0xf347000
	s_addc_u32 s17, s15, 0
	v_lshrrev_b32_e32 v205, 4, v124
	v_lshrrev_b32_e32 v206, 5, v124
	v_lshrrev_b32_e32 v207, 0, v124
	v_xor_b32_e32 v196, v207, v205
	v_and_b32_e32 v196, 1, v196
	v_add_u32_e32 v196, -1, v196
	v_xor_b32_e32 v200, v207, v206
	v_and_b32_e32 v200, 1, v200
	v_add_u32_e32 v200, -1, v200
	v_lshrrev_b32_e32 v207, 1, v124
	v_xor_b32_e32 v197, v207, v205
	v_and_b32_e32 v197, 1, v197
	v_add_u32_e32 v197, -1, v197
	v_xor_b32_e32 v201, v207, v206
	v_and_b32_e32 v201, 1, v201
	v_add_u32_e32 v201, -1, v201
	v_lshrrev_b32_e32 v207, 2, v124
	v_xor_b32_e32 v198, v207, v205
	v_and_b32_e32 v198, 1, v198
	v_add_u32_e32 v198, -1, v198
	v_xor_b32_e32 v202, v207, v206
	v_and_b32_e32 v202, 1, v202
	v_add_u32_e32 v202, -1, v202
	v_lshrrev_b32_e32 v207, 3, v124
	v_xor_b32_e32 v199, v207, v205
	v_and_b32_e32 v199, 1, v199
	v_add_u32_e32 v199, -1, v199
	v_xor_b32_e32 v203, v207, v206
	v_and_b32_e32 v203, 1, v203
	v_add_u32_e32 v203, -1, v203
	v_mov_b32_e32 v204, 16
	s_getpc_b64 s[4:5]
	s_add_u32 s4, s4, _ZL7kStairJ@rel32@lo+4
	s_addc_u32 s5, s5, _ZL7kStairJ@rel32@hi+12
	v_lshlrev_b32_e32 v2, 4, v124
	s_getpc_b64 s[6:7]
	s_add_u32 s6, s6, _ZL7kStairI@rel32@lo+4
	s_addc_u32 s7, s7, _ZL7kStairI@rel32@hi+12
	v_lshl_add_u64 v[4:5], s[16:17], 0, v[4:5]
	global_load_ubyte v6, v124, s[4:5]
	global_load_ubyte v7, v124, s[6:7]
	v_lshl_add_u64 v[4:5], v[4:5], 0, v[2:3]
	global_load_dwordx4 v[112:115], v[4:5], off
	s_movk_i32 s4, 0x3400
	v_mul_lo_u32 v127, v0, s4
	s_add_u32 s36, s14, 0x2d27000
	v_and_b32_e32 v4, 31, v1
	v_and_b32_e32 v5, 8, v1
	v_and_b32_e32 v8, 4, v1
	v_and_b32_e32 v9, 2, v1
	v_and_b32_e32 v10, 1, v1
	v_lshlrev_b32_e32 v1, 1, v1
	v_add_u32_e32 v131, v127, v2
	s_addc_u32 s37, s15, 0
	v_lshlrev_b32_e32 v0, 2, v124
	v_and_b32_e32 v129, 60, v1
	v_and_or_b32 v1, v1, 64, v127
	v_mad_i32_i24 v133, v124, -12, v131
	v_lshl_add_u64 v[118:119], s[16:17], 0, v[2:3]
	v_lshlrev_b32_e32 v2, 3, v4
	s_add_u32 s38, s14, 0x2d37000
	s_mov_b64 s[18:19], 0x17747000
	v_add_u32_e32 v134, 0xc00, v1
	v_add_u32_e32 v135, v133, v0
	v_lshl_add_u64 v[0:1], s[14:15], 0, v[2:3]
	v_or_b32_e32 v136, 0x200, v2
	v_lshlrev_b32_e32 v2, 3, v124
	s_addc_u32 s39, s15, 0
	s_mov_b64 s[20:21], 0x11b47000
	v_mbcnt_lo_u32_b32 v11, -1, 0
	v_lshl_add_u64 v[120:121], v[0:1], 0, s[18:19]
	v_lshl_add_u64 v[0:1], s[14:15], 0, v[2:3]
	s_add_u32 s40, s14, 0xd27000
	s_mov_b64 s[34:35], 0
	s_mov_b32 s47, 0x83ff
	s_movk_i32 s48, 0xffc0
	s_movk_i32 s49, 0x3f80
	s_mov_b32 s50, 0xffff0000
	s_movk_i32 s51, 0x300
	s_mov_b32 s52, 0x378e98ab
	s_mov_b32 s53, 0x3b7cd369
	s_mov_b32 s54, 0xbcc618b2
	s_mov_b32 s55, 0x3dda74e4
	s_mov_b32 s56, 0x3f228afd
	s_mov_b32 s57, 0x3e03c728
	s_mov_b32 s58, 0xbfb8aa3b
	s_mov_b32 s59, 0x42ce8ed0
	s_mov_b32 s60, 0xc2b17218
	v_mov_b32_e32 v125, 0x3ba10414
	s_brev_b32 s61, -2
	s_mov_b32 s62, 0x44800000
	v_bfrev_b32_e32 v126, 1
	v_cmp_gt_u32_e64 s[4:5], 50, v124
	v_lshlrev_b32_e32 v128, 4, v4
	v_cmp_eq_u32_e64 s[6:7], 0, v5
	v_cmp_eq_u32_e64 s[8:9], 0, v8
	v_cmp_eq_u32_e64 s[10:11], 0, v9
	v_cmp_eq_u32_e64 s[12:13], 0, v10
	v_mbcnt_hi_u32_b32 v130, -1, v11
	v_add_u32_e32 v132, 0x400, v127
	v_lshl_add_u64 v[122:123], v[0:1], 0, s[20:21]
	s_addc_u32 s41, s15, 0
	v_mov_b32_e32 v139, 0xb9c68948
	v_mov_b32_e32 v140, 0x7f800000
	s_waitcnt vmcnt(2)
	v_lshl_add_u32 v138, v6, 2, v127
	s_waitcnt vmcnt(1)
	v_lshl_add_u32 v137, v7, 2, v127
	v_ashrrev_i32_e32 v225, 31, v116
	v_mov_b32_e32 v224, v116
	v_lshlrev_b64 v[224:225], 11, v[224:225]
	v_lshl_add_u64 v[224:225], v[120:121], 0, v[224:225]
	global_load_dwordx2 v[208:209], v[224:225], off
	global_load_dwordx2 v[210:211], v[224:225], off offset:256
	global_load_dwordx2 v[212:213], v[224:225], off offset:512
	global_load_dwordx2 v[214:215], v[224:225], off offset:768
	global_load_dwordx2 v[216:217], v[224:225], off offset:1024
	global_load_dwordx2 v[218:219], v[224:225], off offset:1280
	global_load_dwordx2 v[220:221], v[224:225], off offset:1536
	global_load_dwordx2 v[222:223], v[224:225], off offset:1792
	v_readfirstlane_b32 s94, v116
	s_nop 3
.Lg1_group:
	s_mov_b32 s96, 0
.Lg1_phase:
	s_mov_b32 s95, 0
.Lg1_tok:
	s_mul_i32 s71, s95, s33
	s_add_u32 s71, s71, s94
	s_cmp_ge_u32 s71, s46
	s_cbranch_scc1 .Lg1_phase_done
	v_mov_b32_e32 v116, s71
	s_mul_i32 s97, s95, 2560
	s_cmp_lg_u32 s96, 0
	s_cbranch_scc1 .Lg1_rdisp
	v_add_u32_e32 v189, s97, v127
	s_branch .LBB0_978
.Lg1_rdisp:
	v_add_u32_e32 v226, s97, v135
	s_add_u32 s32, s71, s33
	s_add_u32 s97, s95, 1
	s_cmp_lt_u32 s97, 4
	s_cselect_b32 s97, 1, 0
	s_cmp_lt_u32 s32, s46
	s_cselect_b32 s71, 1, 0
	s_and_b32 s97, s97, s71
	s_mul_i32 s71, s33, 4
	s_add_u32 s71, s71, s94
	s_cmp_lt_u32 s71, s46
	s_cselect_b32 s71, s71, s94
	s_cmp_eq_u32 s96, 1
	s_cselect_b32 s71, s94, s71
	s_cmp_lg_u32 s97, 0
	s_cselect_b32 s71, s32, s71
	v_mov_b32_e32 v227, s71
	s_mul_i32 s97, s95, 2560
	s_ff1_i32_b32 s32, s33
	s_add_u32 s32, s32, 2
	s_lshr_b32 s32, s94, s32
	s_add_u32 s71, s96, -1
	s_xor_b32 s32, s32, s71
	s_and_b32 s32, s32, 1
	s_lshl_b32 s71, s32, 8
	s_add_u32 s97, s97, s71
	s_lshl_b32 s71, s32, 6
	s_add_u32 s71, s71, 0x1f
	s_lshl_b32 s32, s32, 6
	s_add_u32 s32, s32, 0xffffffe0
	s_branch .Lg1_rtok
.Lg1_tok_next:
	s_add_u32 s95, s95, 1
	s_cmp_lt_u32 s95, 4
	s_cbranch_scc1 .Lg1_tok
.Lg1_phase_done:
	s_add_u32 s96, s96, 1
	s_cmp_lt_u32 s96, 3
	s_cbranch_scc1 .Lg1_phase
	s_mul_i32 s71, s33, 4
	s_add_u32 s94, s94, s71
	s_cmp_lt_u32 s94, s46
	s_cbranch_scc1 .Lg1_group
	s_branch .LBB0_1038
.LBB0_977:
	s_setprio 0
	s_cmp_lg_u32 s96, 2
	s_cbranch_scc1 .Lg1_tok_next
	s_mul_i32 s97, s95, 2560
	v_add_u32_e32 v6, s97, v135
	s_waitcnt lgkmcnt(0)
	ds_read2st64_b64 v[0:3], v6 offset0:6 offset1:8
	v_lshlrev_b64 v[4:5], 9, v[116:117]
	v_mov_b32_e32 v116, v141
	s_waitcnt lgkmcnt(0)
	v_fma_mixlo_f16 v2, v2, s62, 0
	v_fma_mixhi_f16 v3, v3, s62, 0
	v_lshl_or_b32 v0, v2, 16, v0
	v_and_or_b32 v1, v3, s50, v1
	v_lshl_add_u64 v[2:3], v[122:123], 0, v[4:5]
	global_store_dwordx2 v[2:3], v[0:1], off
	s_waitcnt lgkmcnt(0)
	s_branch .Lg1_tok_next

.LBB0_994:
	s_or_b64 exec, exec, s[16:17]
	v_ashrrev_i32_e32 v5, 31, v2
	v_or_b32_e32 v5, 0x80000000, v5
	v_bitop3_b32 v5, v5, s48, v2 bitop3:0x48
	v_bitop3_b32 v39, v5, 63, v124 bitop3:0x36
	ds_write_b32 v133, v39 offset:2816
	s_waitcnt lgkmcnt(0)
	s_and_b64 s[14:15], exec, vcc
	s_or_b64 s[34:35], s[14:15], s[34:35]
	v_mov_b32_e32 v40, v29
	v_mov_b32_e32 v41, v30
	v_mov_b32_e32 v42, v31
	v_mov_b32_e32 v43, v33
	v_mov_b32_e32 v44, v34
	v_mov_b32_e32 v45, v36
	v_mov_b32_e32 v46, v37
	v_mov_b32_e32 v47, v39
	v_mov_b32_e32 v48, 0
	v_mov_b32_e32 v49, 0
	v_mov_b32_e32 v50, 0
	v_mov_b32_e32 v51, 0
	v_mov_b32_e32 v52, 0
	v_mov_b32_e32 v53, 0
	v_mov_b32_e32 v54, 0
	v_mov_b32_e32 v55, 0
	v_mov_b32_dpp v48, v40 quad_perm:[1,0,3,2] row_mask:0xf bank_mask:0xf
	v_mov_b32_dpp v49, v41 quad_perm:[1,0,3,2] row_mask:0xf bank_mask:0xf
	v_mov_b32_dpp v50, v42 quad_perm:[1,0,3,2] row_mask:0xf bank_mask:0xf
	v_mov_b32_dpp v51, v43 quad_perm:[1,0,3,2] row_mask:0xf bank_mask:0xf
	v_mov_b32_dpp v52, v44 quad_perm:[1,0,3,2] row_mask:0xf bank_mask:0xf
	v_mov_b32_dpp v53, v45 quad_perm:[1,0,3,2] row_mask:0xf bank_mask:0xf
	v_mov_b32_dpp v54, v46 quad_perm:[1,0,3,2] row_mask:0xf bank_mask:0xf
	v_mov_b32_dpp v55, v47 quad_perm:[1,0,3,2] row_mask:0xf bank_mask:0xf
	v_med3_u32 v40, v40, v48, v196
	v_med3_u32 v41, v41, v49, v196
	v_med3_u32 v42, v42, v50, v196
	v_med3_u32 v43, v43, v51, v196
	v_med3_u32 v44, v44, v52, v196
	v_med3_u32 v45, v45, v53, v196
	v_med3_u32 v46, v46, v54, v196
	v_med3_u32 v47, v47, v55, v196
	v_mov_b32_dpp v48, v40 quad_perm:[3,2,1,0] row_mask:0xf bank_mask:0xf
	v_mov_b32_dpp v49, v41 quad_perm:[3,2,1,0] row_mask:0xf bank_mask:0xf
	v_mov_b32_dpp v50, v42 quad_perm:[3,2,1,0] row_mask:0xf bank_mask:0xf
	v_mov_b32_dpp v51, v43 quad_perm:[3,2,1,0] row_mask:0xf bank_mask:0xf
	v_mov_b32_dpp v52, v44 quad_perm:[3,2,1,0] row_mask:0xf bank_mask:0xf
	v_mov_b32_dpp v53, v45 quad_perm:[3,2,1,0] row_mask:0xf bank_mask:0xf
	v_mov_b32_dpp v54, v46 quad_perm:[3,2,1,0] row_mask:0xf bank_mask:0xf
	v_mov_b32_dpp v55, v47 quad_perm:[3,2,1,0] row_mask:0xf bank_mask:0xf
	v_med3_u32 v40, v40, v48, v197
	v_med3_u32 v41, v41, v49, v197
	v_med3_u32 v42, v42, v50, v197
	v_med3_u32 v43, v43, v51, v197
	v_med3_u32 v44, v44, v52, v197
	v_med3_u32 v45, v45, v53, v197
	v_med3_u32 v46, v46, v54, v197
	v_med3_u32 v47, v47, v55, v197
	v_mov_b32_dpp v48, v40 quad_perm:[1,0,3,2] row_mask:0xf bank_mask:0xf
	v_mov_b32_dpp v49, v41 quad_perm:[1,0,3,2] row_mask:0xf bank_mask:0xf
	v_mov_b32_dpp v50, v42 quad_perm:[1,0,3,2] row_mask:0xf bank_mask:0xf
	v_mov_b32_dpp v51, v43 quad_perm:[1,0,3,2] row_mask:0xf bank_mask:0xf
	v_mov_b32_dpp v52, v44 quad_perm:[1,0,3,2] row_mask:0xf bank_mask:0xf
	v_mov_b32_dpp v53, v45 quad_perm:[1,0,3,2] row_mask:0xf bank_mask:0xf
	v_mov_b32_dpp v54, v46 quad_perm:[1,0,3,2] row_mask:0xf bank_mask:0xf
	v_mov_b32_dpp v55, v47 quad_perm:[1,0,3,2] row_mask:0xf bank_mask:0xf
	v_med3_u32 v40, v40, v48, v196
	v_med3_u32 v41, v41, v49, v196
	v_med3_u32 v42, v42, v50, v196
	v_med3_u32 v43, v43, v51, v196
	v_med3_u32 v44, v44, v52, v196
	v_med3_u32 v45, v45, v53, v196
	v_med3_u32 v46, v46, v54, v196
	v_med3_u32 v47, v47, v55, v196
	v_mov_b32_dpp v48, v40 row_half_mirror row_mask:0xf bank_mask:0xf
	v_mov_b32_dpp v49, v41 row_half_mirror row_mask:0xf bank_mask:0xf
	v_mov_b32_dpp v50, v42 row_half_mirror row_mask:0xf bank_mask:0xf
	v_mov_b32_dpp v51, v43 row_half_mirror row_mask:0xf bank_mask:0xf
	v_mov_b32_dpp v52, v44 row_half_mirror row_mask:0xf bank_mask:0xf
	v_mov_b32_dpp v53, v45 row_half_mirror row_mask:0xf bank_mask:0xf
	v_mov_b32_dpp v54, v46 row_half_mirror row_mask:0xf bank_mask:0xf
	v_mov_b32_dpp v55, v47 row_half_mirror row_mask:0xf bank_mask:0xf
	v_med3_u32 v40, v40, v48, v198
	v_med3_u32 v41, v41, v49, v198
	v_med3_u32 v42, v42, v50, v198
	v_med3_u32 v43, v43, v51, v198
	v_med3_u32 v44, v44, v52, v198
	v_med3_u32 v45, v45, v53, v198
	v_med3_u32 v46, v46, v54, v198
	v_med3_u32 v47, v47, v55, v198
	v_mov_b32_dpp v48, v40 quad_perm:[2,3,0,1] row_mask:0xf bank_mask:0xf
	v_mov_b32_dpp v49, v41 quad_perm:[2,3,0,1] row_mask:0xf bank_mask:0xf
	v_mov_b32_dpp v50, v42 quad_perm:[2,3,0,1] row_mask:0xf bank_mask:0xf
	v_mov_b32_dpp v51, v43 quad_perm:[2,3,0,1] row_mask:0xf bank_mask:0xf
	v_mov_b32_dpp v52, v44 quad_perm:[2,3,0,1] row_mask:0xf bank_mask:0xf
	v_mov_b32_dpp v53, v45 quad_perm:[2,3,0,1] row_mask:0xf bank_mask:0xf
	v_mov_b32_dpp v54, v46 quad_perm:[2,3,0,1] row_mask:0xf bank_mask:0xf
	v_mov_b32_dpp v55, v47 quad_perm:[2,3,0,1] row_mask:0xf bank_mask:0xf
	v_med3_u32 v40, v40, v48, v197
	v_med3_u32 v41, v41, v49, v197
	v_med3_u32 v42, v42, v50, v197
	v_med3_u32 v43, v43, v51, v197
	v_med3_u32 v44, v44, v52, v197
	v_med3_u32 v45, v45, v53, v197
	v_med3_u32 v46, v46, v54, v197
	v_med3_u32 v47, v47, v55, v197
	v_mov_b32_dpp v48, v40 quad_perm:[1,0,3,2] row_mask:0xf bank_mask:0xf
	v_mov_b32_dpp v49, v41 quad_perm:[1,0,3,2] row_mask:0xf bank_mask:0xf
	v_mov_b32_dpp v50, v42 quad_perm:[1,0,3,2] row_mask:0xf bank_mask:0xf
	v_mov_b32_dpp v51, v43 quad_perm:[1,0,3,2] row_mask:0xf bank_mask:0xf
	v_mov_b32_dpp v52, v44 quad_perm:[1,0,3,2] row_mask:0xf bank_mask:0xf
	v_mov_b32_dpp v53, v45 quad_perm:[1,0,3,2] row_mask:0xf bank_mask:0xf
	v_mov_b32_dpp v54, v46 quad_perm:[1,0,3,2] row_mask:0xf bank_mask:0xf
	v_mov_b32_dpp v55, v47 quad_perm:[1,0,3,2] row_mask:0xf bank_mask:0xf
	v_med3_u32 v40, v40, v48, v196
	v_med3_u32 v41, v41, v49, v196
	v_med3_u32 v42, v42, v50, v196
	v_med3_u32 v43, v43, v51, v196
	v_med3_u32 v44, v44, v52, v196
	v_med3_u32 v45, v45, v53, v196
	v_med3_u32 v46, v46, v54, v196
	v_med3_u32 v47, v47, v55, v196
	v_mov_b32_dpp v48, v40 row_mirror row_mask:0xf bank_mask:0xf
	v_mov_b32_dpp v49, v41 row_mirror row_mask:0xf bank_mask:0xf
	v_mov_b32_dpp v50, v42 row_mirror row_mask:0xf bank_mask:0xf
	v_mov_b32_dpp v51, v43 row_mirror row_mask:0xf bank_mask:0xf
	v_mov_b32_dpp v52, v44 row_mirror row_mask:0xf bank_mask:0xf
	v_mov_b32_dpp v53, v45 row_mirror row_mask:0xf bank_mask:0xf
	v_mov_b32_dpp v54, v46 row_mirror row_mask:0xf bank_mask:0xf
	v_mov_b32_dpp v55, v47 row_mirror row_mask:0xf bank_mask:0xf
	v_med3_u32 v40, v40, v48, v199
	v_med3_u32 v41, v41, v49, v199
	v_med3_u32 v42, v42, v50, v199
	v_med3_u32 v43, v43, v51, v199
	v_med3_u32 v44, v44, v52, v199
	v_med3_u32 v45, v45, v53, v199
	v_med3_u32 v46, v46, v54, v199
	v_med3_u32 v47, v47, v55, v199
	v_mov_b32_dpp v48, v40 row_shl:4 row_mask:0xf bank_mask:0x5
	v_mov_b32_dpp v49, v41 row_shl:4 row_mask:0xf bank_mask:0x5
	v_mov_b32_dpp v50, v42 row_shl:4 row_mask:0xf bank_mask:0x5
	v_mov_b32_dpp v51, v43 row_shl:4 row_mask:0xf bank_mask:0x5
	v_mov_b32_dpp v52, v44 row_shl:4 row_mask:0xf bank_mask:0x5
	v_mov_b32_dpp v53, v45 row_shl:4 row_mask:0xf bank_mask:0x5
	v_mov_b32_dpp v54, v46 row_shl:4 row_mask:0xf bank_mask:0x5
	v_mov_b32_dpp v55, v47 row_shl:4 row_mask:0xf bank_mask:0x5
	v_mov_b32_dpp v48, v40 row_shr:4 row_mask:0xf bank_mask:0xa
	v_mov_b32_dpp v49, v41 row_shr:4 row_mask:0xf bank_mask:0xa
	v_mov_b32_dpp v50, v42 row_shr:4 row_mask:0xf bank_mask:0xa
	v_mov_b32_dpp v51, v43 row_shr:4 row_mask:0xf bank_mask:0xa
	v_mov_b32_dpp v52, v44 row_shr:4 row_mask:0xf bank_mask:0xa
	v_mov_b32_dpp v53, v45 row_shr:4 row_mask:0xf bank_mask:0xa
	v_mov_b32_dpp v54, v46 row_shr:4 row_mask:0xf bank_mask:0xa
	v_mov_b32_dpp v55, v47 row_shr:4 row_mask:0xf bank_mask:0xa
	v_med3_u32 v40, v40, v48, v198
	v_med3_u32 v41, v41, v49, v198
	v_med3_u32 v42, v42, v50, v198
	v_med3_u32 v43, v43, v51, v198
	v_med3_u32 v44, v44, v52, v198
	v_med3_u32 v45, v45, v53, v198
	v_med3_u32 v46, v46, v54, v198
	v_med3_u32 v47, v47, v55, v198
	v_mov_b32_dpp v48, v40 quad_perm:[2,3,0,1] row_mask:0xf bank_mask:0xf
	v_mov_b32_dpp v49, v41 quad_perm:[2,3,0,1] row_mask:0xf bank_mask:0xf
	v_mov_b32_dpp v50, v42 quad_perm:[2,3,0,1] row_mask:0xf bank_mask:0xf
	v_mov_b32_dpp v51, v43 quad_perm:[2,3,0,1] row_mask:0xf bank_mask:0xf
	v_mov_b32_dpp v52, v44 quad_perm:[2,3,0,1] row_mask:0xf bank_mask:0xf
	v_mov_b32_dpp v53, v45 quad_perm:[2,3,0,1] row_mask:0xf bank_mask:0xf
	v_mov_b32_dpp v54, v46 quad_perm:[2,3,0,1] row_mask:0xf bank_mask:0xf
	v_mov_b32_dpp v55, v47 quad_perm:[2,3,0,1] row_mask:0xf bank_mask:0xf
	v_med3_u32 v40, v40, v48, v197
	v_med3_u32 v41, v41, v49, v197
	v_med3_u32 v42, v42, v50, v197
	v_med3_u32 v43, v43, v51, v197
	v_med3_u32 v44, v44, v52, v197
	v_med3_u32 v45, v45, v53, v197
	v_med3_u32 v46, v46, v54, v197
	v_med3_u32 v47, v47, v55, v197
	v_mov_b32_dpp v48, v40 quad_perm:[1,0,3,2] row_mask:0xf bank_mask:0xf
	v_mov_b32_dpp v49, v41 quad_perm:[1,0,3,2] row_mask:0xf bank_mask:0xf
	v_mov_b32_dpp v50, v42 quad_perm:[1,0,3,2] row_mask:0xf bank_mask:0xf
	v_mov_b32_dpp v51, v43 quad_perm:[1,0,3,2] row_mask:0xf bank_mask:0xf
	v_mov_b32_dpp v52, v44 quad_perm:[1,0,3,2] row_mask:0xf bank_mask:0xf
	v_mov_b32_dpp v53, v45 quad_perm:[1,0,3,2] row_mask:0xf bank_mask:0xf
	v_mov_b32_dpp v54, v46 quad_perm:[1,0,3,2] row_mask:0xf bank_mask:0xf
	v_mov_b32_dpp v55, v47 quad_perm:[1,0,3,2] row_mask:0xf bank_mask:0xf
	v_med3_u32 v40, v40, v48, v196
	v_med3_u32 v41, v41, v49, v196
	v_med3_u32 v42, v42, v50, v196
	v_med3_u32 v43, v43, v51, v196
	v_med3_u32 v44, v44, v52, v196
	v_med3_u32 v45, v45, v53, v196
	v_med3_u32 v46, v46, v54, v196
	v_med3_u32 v47, v47, v55, v196
	v_mov_b32_e32 v56, v40
	v_mov_b32_e32 v57, v41
	v_mov_b32_e32 v58, v42
	v_mov_b32_e32 v59, v43
	v_mov_b32_e32 v60, v44
	v_mov_b32_e32 v61, v45
	v_mov_b32_e32 v62, v46
	v_mov_b32_e32 v63, v47
	v_permlane16_swap_b32_e32 v40, v56
	v_permlane16_swap_b32_e32 v41, v57
	v_permlane16_swap_b32_e32 v42, v58
	v_permlane16_swap_b32_e32 v43, v59
	v_permlane16_swap_b32_e32 v44, v60
	v_permlane16_swap_b32_e32 v45, v61
	v_permlane16_swap_b32_e32 v46, v62
	v_permlane16_swap_b32_e32 v47, v63
	v_max_u32_e32 v40, v40, v56
	v_max_u32_e32 v41, v41, v57
	v_max_u32_e32 v42, v42, v58
	v_max_u32_e32 v43, v43, v59
	v_max_u32_e32 v44, v44, v60
	v_max_u32_e32 v45, v45, v61
	v_max_u32_e32 v46, v46, v62
	v_max_u32_e32 v47, v47, v63
	v_mov_b32_dpp v48, v40 row_ror:8 row_mask:0xf bank_mask:0xf
	v_mov_b32_dpp v49, v41 row_ror:8 row_mask:0xf bank_mask:0xf
	v_mov_b32_dpp v50, v42 row_ror:8 row_mask:0xf bank_mask:0xf
	v_mov_b32_dpp v51, v43 row_ror:8 row_mask:0xf bank_mask:0xf
	v_mov_b32_dpp v52, v44 row_ror:8 row_mask:0xf bank_mask:0xf
	v_mov_b32_dpp v53, v45 row_ror:8 row_mask:0xf bank_mask:0xf
	v_mov_b32_dpp v54, v46 row_ror:8 row_mask:0xf bank_mask:0xf
	v_mov_b32_dpp v55, v47 row_ror:8 row_mask:0xf bank_mask:0xf
	v_med3_u32 v40, v40, v48, v203
	v_med3_u32 v41, v41, v49, v203
	v_med3_u32 v42, v42, v50, v203
	v_med3_u32 v43, v43, v51, v203
	v_med3_u32 v44, v44, v52, v203
	v_med3_u32 v45, v45, v53, v203
	v_med3_u32 v46, v46, v54, v203
	v_med3_u32 v47, v47, v55, v203
	v_mov_b32_dpp v48, v40 row_shl:4 row_mask:0xf bank_mask:0x5
	v_mov_b32_dpp v49, v41 row_shl:4 row_mask:0xf bank_mask:0x5
	v_mov_b32_dpp v50, v42 row_shl:4 row_mask:0xf bank_mask:0x5
	v_mov_b32_dpp v51, v43 row_shl:4 row_mask:0xf bank_mask:0x5
	v_mov_b32_dpp v52, v44 row_shl:4 row_mask:0xf bank_mask:0x5
	v_mov_b32_dpp v53, v45 row_shl:4 row_mask:0xf bank_mask:0x5
	v_mov_b32_dpp v54, v46 row_shl:4 row_mask:0xf bank_mask:0x5
	v_mov_b32_dpp v55, v47 row_shl:4 row_mask:0xf bank_mask:0x5
	v_mov_b32_dpp v48, v40 row_shr:4 row_mask:0xf bank_mask:0xa
	v_mov_b32_dpp v49, v41 row_shr:4 row_mask:0xf bank_mask:0xa
	v_mov_b32_dpp v50, v42 row_shr:4 row_mask:0xf bank_mask:0xa
	v_mov_b32_dpp v51, v43 row_shr:4 row_mask:0xf bank_mask:0xa
	v_mov_b32_dpp v52, v44 row_shr:4 row_mask:0xf bank_mask:0xa
	v_mov_b32_dpp v53, v45 row_shr:4 row_mask:0xf bank_mask:0xa
	v_mov_b32_dpp v54, v46 row_shr:4 row_mask:0xf bank_mask:0xa
	v_mov_b32_dpp v55, v47 row_shr:4 row_mask:0xf bank_mask:0xa
	v_med3_u32 v40, v40, v48, v202
	v_med3_u32 v41, v41, v49, v202
	v_med3_u32 v42, v42, v50, v202
	v_med3_u32 v43, v43, v51, v202
	v_med3_u32 v44, v44, v52, v202
	v_med3_u32 v45, v45, v53, v202
	v_med3_u32 v46, v46, v54, v202
	v_med3_u32 v47, v47, v55, v202
	v_mov_b32_dpp v48, v40 quad_perm:[2,3,0,1] row_mask:0xf bank_mask:0xf
	v_mov_b32_dpp v49, v41 quad_perm:[2,3,0,1] row_mask:0xf bank_mask:0xf
	v_mov_b32_dpp v50, v42 quad_perm:[2,3,0,1] row_mask:0xf bank_mask:0xf
	v_mov_b32_dpp v51, v43 quad_perm:[2,3,0,1] row_mask:0xf bank_mask:0xf
	v_mov_b32_dpp v52, v44 quad_perm:[2,3,0,1] row_mask:0xf bank_mask:0xf
	v_mov_b32_dpp v53, v45 quad_perm:[2,3,0,1] row_mask:0xf bank_mask:0xf
	v_mov_b32_dpp v54, v46 quad_perm:[2,3,0,1] row_mask:0xf bank_mask:0xf
	v_mov_b32_dpp v55, v47 quad_perm:[2,3,0,1] row_mask:0xf bank_mask:0xf
	v_med3_u32 v40, v40, v48, v201
	v_med3_u32 v41, v41, v49, v201
	v_med3_u32 v42, v42, v50, v201
	v_med3_u32 v43, v43, v51, v201
	v_med3_u32 v44, v44, v52, v201
	v_med3_u32 v45, v45, v53, v201
	v_med3_u32 v46, v46, v54, v201
	v_med3_u32 v47, v47, v55, v201
	v_mov_b32_dpp v48, v40 quad_perm:[1,0,3,2] row_mask:0xf bank_mask:0xf
	v_mov_b32_dpp v49, v41 quad_perm:[1,0,3,2] row_mask:0xf bank_mask:0xf
	v_mov_b32_dpp v50, v42 quad_perm:[1,0,3,2] row_mask:0xf bank_mask:0xf
	v_mov_b32_dpp v51, v43 quad_perm:[1,0,3,2] row_mask:0xf bank_mask:0xf
	v_mov_b32_dpp v52, v44 quad_perm:[1,0,3,2] row_mask:0xf bank_mask:0xf
	v_mov_b32_dpp v53, v45 quad_perm:[1,0,3,2] row_mask:0xf bank_mask:0xf
	v_mov_b32_dpp v54, v46 quad_perm:[1,0,3,2] row_mask:0xf bank_mask:0xf
	v_mov_b32_dpp v55, v47 quad_perm:[1,0,3,2] row_mask:0xf bank_mask:0xf
	v_med3_u32 v40, v40, v48, v200
	v_med3_u32 v41, v41, v49, v200
	v_med3_u32 v42, v42, v50, v200
	v_med3_u32 v43, v43, v51, v200
	v_med3_u32 v44, v44, v52, v200
	v_med3_u32 v45, v45, v53, v200
	v_med3_u32 v46, v46, v54, v200
	v_med3_u32 v47, v47, v55, v200
	v_mov_b32_e32 v56, v40
	v_mov_b32_e32 v57, v41
	v_mov_b32_e32 v58, v42
	v_mov_b32_e32 v59, v43
	v_mov_b32_e32 v60, v44
	v_mov_b32_e32 v61, v45
	v_mov_b32_e32 v62, v46
	v_mov_b32_e32 v63, v47
	v_permlane32_swap_b32_e32 v40, v56
	v_permlane32_swap_b32_e32 v41, v57
	v_permlane32_swap_b32_e32 v42, v58
	v_permlane32_swap_b32_e32 v43, v59
	v_permlane32_swap_b32_e32 v44, v60
	v_permlane32_swap_b32_e32 v45, v61
	v_permlane32_swap_b32_e32 v46, v62
	v_permlane32_swap_b32_e32 v47, v63
	v_max_u32_e32 v40, v40, v56
	v_max_u32_e32 v41, v41, v57
	v_max_u32_e32 v42, v42, v58
	v_max_u32_e32 v43, v43, v59
	v_max_u32_e32 v44, v44, v60
	v_max_u32_e32 v45, v45, v61
	v_max_u32_e32 v46, v46, v62
	v_max_u32_e32 v47, v47, v63
	v_min_u32_dpp v40, v40, v40 quad_perm:[1,0,3,2] row_mask:0xf bank_mask:0xf
	v_min_u32_dpp v41, v41, v41 quad_perm:[1,0,3,2] row_mask:0xf bank_mask:0xf
	v_min_u32_dpp v42, v42, v42 quad_perm:[1,0,3,2] row_mask:0xf bank_mask:0xf
	v_min_u32_dpp v43, v43, v43 quad_perm:[1,0,3,2] row_mask:0xf bank_mask:0xf
	v_min_u32_dpp v44, v44, v44 quad_perm:[1,0,3,2] row_mask:0xf bank_mask:0xf
	v_min_u32_dpp v45, v45, v45 quad_perm:[1,0,3,2] row_mask:0xf bank_mask:0xf
	v_min_u32_dpp v46, v46, v46 quad_perm:[1,0,3,2] row_mask:0xf bank_mask:0xf
	v_min_u32_dpp v47, v47, v47 quad_perm:[1,0,3,2] row_mask:0xf bank_mask:0xf
	v_min_u32_dpp v40, v40, v40 quad_perm:[2,3,0,1] row_mask:0xf bank_mask:0xf
	v_min_u32_dpp v41, v41, v41 quad_perm:[2,3,0,1] row_mask:0xf bank_mask:0xf
	v_min_u32_dpp v42, v42, v42 quad_perm:[2,3,0,1] row_mask:0xf bank_mask:0xf
	v_min_u32_dpp v43, v43, v43 quad_perm:[2,3,0,1] row_mask:0xf bank_mask:0xf
	v_min_u32_dpp v44, v44, v44 quad_perm:[2,3,0,1] row_mask:0xf bank_mask:0xf
	v_min_u32_dpp v45, v45, v45 quad_perm:[2,3,0,1] row_mask:0xf bank_mask:0xf
	v_min_u32_dpp v46, v46, v46 quad_perm:[2,3,0,1] row_mask:0xf bank_mask:0xf
	v_min_u32_dpp v47, v47, v47 quad_perm:[2,3,0,1] row_mask:0xf bank_mask:0xf
	v_min_u32_dpp v40, v40, v40 row_half_mirror row_mask:0xf bank_mask:0xf
	v_min_u32_dpp v41, v41, v41 row_half_mirror row_mask:0xf bank_mask:0xf
	v_min_u32_dpp v42, v42, v42 row_half_mirror row_mask:0xf bank_mask:0xf
	v_min_u32_dpp v43, v43, v43 row_half_mirror row_mask:0xf bank_mask:0xf
	v_min_u32_dpp v44, v44, v44 row_half_mirror row_mask:0xf bank_mask:0xf
	v_min_u32_dpp v45, v45, v45 row_half_mirror row_mask:0xf bank_mask:0xf
	v_min_u32_dpp v46, v46, v46 row_half_mirror row_mask:0xf bank_mask:0xf
	v_min_u32_dpp v47, v47, v47 row_half_mirror row_mask:0xf bank_mask:0xf
	v_min_u32_dpp v40, v40, v40 row_mirror row_mask:0xf bank_mask:0xf
	v_min_u32_dpp v41, v41, v41 row_mirror row_mask:0xf bank_mask:0xf
	v_min_u32_dpp v42, v42, v42 row_mirror row_mask:0xf bank_mask:0xf
	v_min_u32_dpp v43, v43, v43 row_mirror row_mask:0xf bank_mask:0xf
	v_min_u32_dpp v44, v44, v44 row_mirror row_mask:0xf bank_mask:0xf
	v_min_u32_dpp v45, v45, v45 row_mirror row_mask:0xf bank_mask:0xf
	v_min_u32_dpp v46, v46, v46 row_mirror row_mask:0xf bank_mask:0xf
	v_min_u32_dpp v47, v47, v47 row_mirror row_mask:0xf bank_mask:0xf
	v_readlane_b32 s80, v40, 0
	v_readlane_b32 s81, v41, 0
	v_readlane_b32 s82, v42, 0
	v_readlane_b32 s83, v43, 0
	v_readlane_b32 s84, v44, 0
	v_readlane_b32 s85, v45, 0
	v_readlane_b32 s86, v46, 0
	v_readlane_b32 s87, v47, 0
	v_cmp_gt_u32_e64 s[66:67], s80, v29
	v_cmp_gt_u32_e64 s[68:69], s81, v30
	v_cmp_gt_u32_e64 s[72:73], s82, v31
	v_cmp_gt_u32_e64 s[74:75], s83, v33
	v_cmp_gt_u32_e64 s[76:77], s84, v34
	v_cmp_gt_u32_e64 s[78:79], s85, v36
	v_cmp_gt_u32_e64 s[88:89], s86, v37
	v_cmp_gt_u32_e64 s[90:91], s87, v39
	v_cndmask_b32_e64 v38, 0, v204, s[66:67]
	v_cndmask_b32_e64 v35, 0, v204, s[68:69]
	v_cndmask_b32_e64 v32, 0, v204, s[72:73]
	v_cndmask_b32_e64 v28, 0, v204, s[74:75]
	v_cndmask_b32_e64 v24, 0, v204, s[76:77]
	v_cndmask_b32_e64 v19, 0, v204, s[78:79]
	v_cndmask_b32_e64 v12, 0, v204, s[88:89]
	v_cndmask_b32_e64 v5, 0, v204, s[90:91]
	s_mov_b32 s77, 0
	s_movk_i32 s78, 0x7f
	v_readfirstlane_b32 s14, v27
	v_cmp_gt_i32_e32 vcc, 16, v38
	v_mov_b32_e32 v143, 0
	v_subrev_f32_e32 v27, s14, v27
	v_mul_f32_e32 v27, 0x3fb8aa3b, v27
	v_exp_f32_e32 v27, v27
	s_and_b64 s[14:15], s[4:5], vcc
	v_lshl_add_u32 v142, v38, 2, v127
	v_xor_b32_e32 v184, v25, v26
	v_and_b32_e32 v184, 64, v184
	v_cmp_eq_u32_e32 vcc, 0, v184
	s_and_b64 s[72:73], vcc, s[14:15]
	s_andn2_b64 s[74:75], s[14:15], vcc
	v_mbcnt_lo_u32_b32 v184, s72, 0
	v_mbcnt_hi_u32_b32 v184, s73, v184
	v_mbcnt_lo_u32_b32 v185, s74, 0
	v_mbcnt_hi_u32_b32 v185, s75, v185
	v_add_u32_e32 v184, s77, v184
	v_sub_u32_e32 v185, s78, v185
	v_cndmask_b32_e32 v184, v185, v184, vcc
	v_lshl_add_u32 v142, v184, 2, v189
	s_bcnt1_i32_b64 s76, s[72:73]
	s_add_u32 s77, s77, s76
	s_bcnt1_i32_b64 s76, s[74:75]
	s_sub_u32 s78, s78, s76
	v_mov_b32_e32 v144, 0
	v_cndmask_b32_e64 v29, 0, v27, s[14:15]
	v_mov_b32_e32 v30, v29
	s_nop 1
	v_permlane32_swap_b32_e32 v29, v30
	v_add_f32_e32 v29, v29, v30
	v_mov_b32_e32 v30, v29
	s_nop 1
	v_permlane16_swap_b32_e32 v29, v30
	v_add_f32_e32 v29, v29, v30
	v_mov_b32_e32 v145, 0
	s_nop 0
	v_add_f32_dpp v29, v29, v29 row_ror:8 row_mask:0xf bank_mask:0xf bound_ctrl:1
	s_nop 1
	v_add_f32_dpp v29, v29, v29 row_ror:4 row_mask:0xf bank_mask:0xf bound_ctrl:1
	s_nop 1
	v_add_f32_dpp v29, v29, v29 quad_perm:[2,3,0,1] row_mask:0xf bank_mask:0xf bound_ctrl:1
	s_nop 1
	v_mov_b32_dpp v30, v29 quad_perm:[1,0,3,2] row_mask:0xf bank_mask:0xf bound_ctrl:1
	s_and_saveexec_b64 s[16:17], s[14:15]
	s_cbranch_execz .LBB0_998
	v_lshlrev_b32_e32 v25, 7, v25
	v_and_b32_e32 v26, 0x7f, v26
	v_and_or_b32 v25, v25, s49, v26
	v_add_f32_e32 v26, v29, v30
	v_div_scale_f32 v29, s[18:19], v26, v26, v27
	v_rcp_f32_e32 v30, v29
	s_nop 0
	v_fma_f32 v31, -v29, v30, 1.0
	v_fmac_f32_e32 v30, v31, v30
	v_div_scale_f32 v31, vcc, v27, v26, v27
	v_mul_f32_e32 v33, v31, v30
	v_fma_f32 v34, -v29, v33, v31
	v_fmac_f32_e32 v33, v34, v30
	v_fma_f32 v29, -v29, v33, v31
	v_div_fmas_f32 v29, v29, v30, v33
	v_div_fixup_f32 v26, v29, v26, v27
	ds_write2st64_b32 v142, v25, v26 offset0:12 offset1:14
.LBB0_998:
	s_or_b64 exec, exec, s[16:17]
	v_readfirstlane_b32 s16, v23
	v_cmp_gt_i32_e32 vcc, 16, v35
	v_lshl_add_u32 v27, v35, 2, v127
	v_subrev_f32_e32 v23, s16, v23
	v_mul_f32_e32 v23, 0x3fb8aa3b, v23
	v_exp_f32_e32 v23, v23
	s_and_b64 s[16:17], s[4:5], vcc
	v_add_u32_e32 v146, 64, v27
	v_xor_b32_e32 v184, v20, v21
	v_and_b32_e32 v184, 64, v184
	v_cmp_eq_u32_e32 vcc, 0, v184
	s_and_b64 s[72:73], vcc, s[16:17]
	s_andn2_b64 s[74:75], s[16:17], vcc
	v_mbcnt_lo_u32_b32 v184, s72, 0
	v_mbcnt_hi_u32_b32 v184, s73, v184
	v_mbcnt_lo_u32_b32 v185, s74, 0
	v_mbcnt_hi_u32_b32 v185, s75, v185
	v_add_u32_e32 v184, s77, v184
	v_sub_u32_e32 v185, s78, v185
	v_cndmask_b32_e32 v184, v185, v184, vcc
	v_lshl_add_u32 v146, v184, 2, v189
	s_bcnt1_i32_b64 s76, s[72:73]
	s_add_u32 s77, s77, s76
	s_bcnt1_i32_b64 s76, s[74:75]
	s_sub_u32 s78, s78, s76
	v_mov_b32_e32 v147, 0
	v_cndmask_b32_e64 v25, 0, v23, s[16:17]
	v_mov_b32_e32 v26, v25
	s_nop 1
	v_permlane32_swap_b32_e32 v25, v26
	v_add_f32_e32 v25, v25, v26
	v_mov_b32_e32 v26, v25
	s_nop 1
	v_permlane16_swap_b32_e32 v25, v26
	v_add_f32_e32 v25, v25, v26
	s_nop 1
	v_add_f32_dpp v25, v25, v25 row_ror:8 row_mask:0xf bank_mask:0xf bound_ctrl:1
	s_nop 1
	v_add_f32_dpp v25, v25, v25 row_ror:4 row_mask:0xf bank_mask:0xf bound_ctrl:1
	s_nop 1
	v_add_f32_dpp v25, v25, v25 quad_perm:[2,3,0,1] row_mask:0xf bank_mask:0xf bound_ctrl:1
	s_nop 1
	v_mov_b32_dpp v26, v25 quad_perm:[1,0,3,2] row_mask:0xf bank_mask:0xf bound_ctrl:1
	s_and_saveexec_b64 s[18:19], s[16:17]
	s_cbranch_execz .LBB0_1000
	v_lshlrev_b32_e32 v20, 7, v20
	v_and_b32_e32 v21, 0x7f, v21
	v_and_or_b32 v20, v20, s49, v21
	v_add_f32_e32 v21, v25, v26
	v_div_scale_f32 v25, s[20:21], v21, v21, v23
	v_rcp_f32_e32 v26, v25
	s_nop 0
	v_fma_f32 v27, -v25, v26, 1.0
	v_fmac_f32_e32 v26, v27, v26
	v_div_scale_f32 v27, vcc, v23, v21, v23
	v_mul_f32_e32 v29, v27, v26
	v_fma_f32 v30, -v25, v29, v27
	v_fmac_f32_e32 v29, v30, v26
	v_fma_f32 v25, -v25, v29, v27
	v_div_fmas_f32 v25, v25, v26, v29
	v_div_fixup_f32 v21, v25, v21, v23
	ds_write2st64_b32 v146, v20, v21 offset0:12 offset1:14
.LBB0_1000:
	s_or_b64 exec, exec, s[18:19]
	v_readfirstlane_b32 s18, v22
	v_cmp_gt_i32_e32 vcc, 16, v32
	v_lshl_add_u32 v23, v32, 2, v127
	v_subrev_f32_e32 v20, s18, v22
	v_mul_f32_e32 v20, 0x3fb8aa3b, v20
	v_exp_f32_e32 v20, v20
	s_and_b64 s[18:19], s[4:5], vcc
	v_mov_b32_e32 v149, 0
	v_add_u32_e32 v148, 0x80, v23
	v_xor_b32_e32 v184, v17, v18
	v_and_b32_e32 v184, 64, v184
	v_cmp_eq_u32_e32 vcc, 0, v184
	s_and_b64 s[72:73], vcc, s[18:19]
	s_andn2_b64 s[74:75], s[18:19], vcc
	v_mbcnt_lo_u32_b32 v184, s72, 0
	v_mbcnt_hi_u32_b32 v184, s73, v184
	v_mbcnt_lo_u32_b32 v185, s74, 0
	v_mbcnt_hi_u32_b32 v185, s75, v185
	v_add_u32_e32 v184, s77, v184
	v_sub_u32_e32 v185, s78, v185
	v_cndmask_b32_e32 v184, v185, v184, vcc
	v_lshl_add_u32 v148, v184, 2, v189
	s_bcnt1_i32_b64 s76, s[72:73]
	s_add_u32 s77, s77, s76
	s_bcnt1_i32_b64 s76, s[74:75]
	s_sub_u32 s78, s78, s76
	v_cndmask_b32_e64 v21, 0, v20, s[18:19]
	v_mov_b32_e32 v22, v21
	s_nop 1
	v_permlane32_swap_b32_e32 v21, v22
	v_add_f32_e32 v21, v21, v22
	v_mov_b32_e32 v22, v21
	s_nop 1
	v_permlane16_swap_b32_e32 v21, v22
	v_add_f32_e32 v21, v21, v22
	v_mov_b32_e32 v150, 0
	v_mov_b32_e32 v151, 0
	v_add_f32_dpp v21, v21, v21 row_ror:8 row_mask:0xf bank_mask:0xf bound_ctrl:1
	s_nop 1
	v_add_f32_dpp v21, v21, v21 row_ror:4 row_mask:0xf bank_mask:0xf bound_ctrl:1
	s_nop 1
	v_add_f32_dpp v21, v21, v21 quad_perm:[2,3,0,1] row_mask:0xf bank_mask:0xf bound_ctrl:1
	s_nop 1
	v_mov_b32_dpp v22, v21 quad_perm:[1,0,3,2] row_mask:0xf bank_mask:0xf bound_ctrl:1
	s_and_saveexec_b64 s[20:21], s[18:19]
	s_cbranch_execz .LBB0_1002
	v_lshlrev_b32_e32 v17, 7, v17
	v_and_b32_e32 v18, 0x7f, v18
	v_and_or_b32 v17, v17, s49, v18
	v_add_f32_e32 v18, v21, v22
	v_div_scale_f32 v21, s[22:23], v18, v18, v20
	v_rcp_f32_e32 v22, v21
	s_nop 0
	v_fma_f32 v23, -v21, v22, 1.0
	v_fmac_f32_e32 v22, v23, v22
	v_div_scale_f32 v23, vcc, v20, v18, v20
	v_mul_f32_e32 v25, v23, v22
	v_fma_f32 v26, -v21, v25, v23
	v_fmac_f32_e32 v25, v26, v22
	v_fma_f32 v21, -v21, v25, v23
	v_div_fmas_f32 v21, v21, v22, v25
	v_div_fixup_f32 v18, v21, v18, v20
	ds_write2st64_b32 v148, v17, v18 offset0:12 offset1:14
.LBB0_1002:
	s_or_b64 exec, exec, s[20:21]
	v_readfirstlane_b32 s20, v16
	v_cmp_gt_i32_e32 vcc, 16, v28
	v_lshl_add_u32 v20, v28, 2, v127
	v_subrev_f32_e32 v16, s20, v16
	v_mul_f32_e32 v16, 0x3fb8aa3b, v16
	v_exp_f32_e32 v16, v16
	s_and_b64 s[20:21], s[4:5], vcc
	v_add_u32_e32 v152, 0xc0, v20
	v_xor_b32_e32 v184, v13, v14
	v_and_b32_e32 v184, 64, v184
	v_cmp_eq_u32_e32 vcc, 0, v184
	s_and_b64 s[72:73], vcc, s[20:21]
	s_andn2_b64 s[74:75], s[20:21], vcc
	v_mbcnt_lo_u32_b32 v184, s72, 0
	v_mbcnt_hi_u32_b32 v184, s73, v184
	v_mbcnt_lo_u32_b32 v185, s74, 0
	v_mbcnt_hi_u32_b32 v185, s75, v185
	v_add_u32_e32 v184, s77, v184
	v_sub_u32_e32 v185, s78, v185
	v_cndmask_b32_e32 v184, v185, v184, vcc
	v_lshl_add_u32 v152, v184, 2, v189
	s_bcnt1_i32_b64 s76, s[72:73]
	s_add_u32 s77, s77, s76
	s_bcnt1_i32_b64 s76, s[74:75]
	s_sub_u32 s78, s78, s76
	v_mov_b32_e32 v153, 0
	v_cndmask_b32_e64 v17, 0, v16, s[20:21]
	v_mov_b32_e32 v18, v17
	s_nop 1
	v_permlane32_swap_b32_e32 v17, v18
	v_add_f32_e32 v17, v17, v18
	v_mov_b32_e32 v18, v17
	s_nop 1
	v_permlane16_swap_b32_e32 v17, v18
	v_add_f32_e32 v17, v17, v18
	s_nop 1
	v_add_f32_dpp v17, v17, v17 row_ror:8 row_mask:0xf bank_mask:0xf bound_ctrl:1
	s_nop 1
	v_add_f32_dpp v17, v17, v17 row_ror:4 row_mask:0xf bank_mask:0xf bound_ctrl:1
	s_nop 1
	v_add_f32_dpp v17, v17, v17 quad_perm:[2,3,0,1] row_mask:0xf bank_mask:0xf bound_ctrl:1
	s_nop 1
	v_mov_b32_dpp v18, v17 quad_perm:[1,0,3,2] row_mask:0xf bank_mask:0xf bound_ctrl:1
	s_and_saveexec_b64 s[22:23], s[20:21]
	s_cbranch_execz .LBB0_1004
	v_lshlrev_b32_e32 v13, 7, v13
	v_and_b32_e32 v14, 0x7f, v14
	v_and_or_b32 v13, v13, s49, v14
	v_add_f32_e32 v14, v17, v18
	v_div_scale_f32 v17, s[24:25], v14, v14, v16
	v_rcp_f32_e32 v18, v17
	s_nop 0
	v_fma_f32 v20, -v17, v18, 1.0
	v_fmac_f32_e32 v18, v20, v18
	v_div_scale_f32 v20, vcc, v16, v14, v16
	v_mul_f32_e32 v21, v20, v18
	v_fma_f32 v22, -v17, v21, v20
	v_fmac_f32_e32 v21, v22, v18
	v_fma_f32 v17, -v17, v21, v20
	v_div_fmas_f32 v17, v17, v18, v21
	v_div_fixup_f32 v14, v17, v14, v16
	ds_write2st64_b32 v152, v13, v14 offset0:12 offset1:14
.LBB0_1004:
	s_or_b64 exec, exec, s[22:23]
	v_readfirstlane_b32 s22, v15
	v_cmp_gt_i32_e32 vcc, 16, v24
	v_mov_b32_e32 v155, 0
	v_subrev_f32_e32 v13, s22, v15
	v_mul_f32_e32 v13, 0x3fb8aa3b, v13
	v_exp_f32_e32 v13, v13
	s_and_b64 s[22:23], s[4:5], vcc
	v_lshl_add_u32 v154, v24, 2, v127
	v_xor_b32_e32 v184, v10, v11
	v_and_b32_e32 v184, 64, v184
	v_cmp_eq_u32_e32 vcc, 0, v184
	s_and_b64 s[72:73], vcc, s[22:23]
	s_andn2_b64 s[74:75], s[22:23], vcc
	v_mbcnt_lo_u32_b32 v184, s72, 0
	v_mbcnt_hi_u32_b32 v184, s73, v184
	v_mbcnt_lo_u32_b32 v185, s74, 0
	v_mbcnt_hi_u32_b32 v185, s75, v185
	v_add_u32_e32 v184, s77, v184
	v_sub_u32_e32 v185, s78, v185
	v_cndmask_b32_e32 v184, v185, v184, vcc
	v_lshl_add_u32 v154, v184, 2, v189
	s_bcnt1_i32_b64 s76, s[72:73]
	s_add_u32 s77, s77, s76
	s_bcnt1_i32_b64 s76, s[74:75]
	s_sub_u32 s78, s78, s76
	v_mov_b32_e32 v156, 0
	v_cndmask_b32_e64 v14, 0, v13, s[22:23]
	v_mov_b32_e32 v15, v14
	s_nop 1
	v_permlane32_swap_b32_e32 v14, v15
	v_add_f32_e32 v14, v14, v15
	v_mov_b32_e32 v15, v14
	s_nop 1
	v_permlane16_swap_b32_e32 v14, v15
	v_add_f32_e32 v14, v14, v15
	v_mov_b32_e32 v157, 0
	s_nop 0
	v_add_f32_dpp v14, v14, v14 row_ror:8 row_mask:0xf bank_mask:0xf bound_ctrl:1
	s_nop 1
	v_add_f32_dpp v14, v14, v14 row_ror:4 row_mask:0xf bank_mask:0xf bound_ctrl:1
	s_nop 1
	v_add_f32_dpp v14, v14, v14 quad_perm:[2,3,0,1] row_mask:0xf bank_mask:0xf bound_ctrl:1
	s_nop 1
	v_mov_b32_dpp v15, v14 quad_perm:[1,0,3,2] row_mask:0xf bank_mask:0xf bound_ctrl:1
	s_and_saveexec_b64 s[24:25], s[22:23]
	s_cbranch_execz .LBB0_1006
	v_lshlrev_b32_e32 v10, 7, v10
	v_and_b32_e32 v11, 0x7f, v11
	v_and_or_b32 v10, v10, s49, v11
	v_add_f32_e32 v11, v14, v15
	v_div_scale_f32 v14, s[26:27], v11, v11, v13
	v_rcp_f32_e32 v15, v14
	s_nop 0
	v_fma_f32 v16, -v14, v15, 1.0
	v_fmac_f32_e32 v15, v16, v15
	v_div_scale_f32 v16, vcc, v13, v11, v13
	v_mul_f32_e32 v17, v16, v15
	v_fma_f32 v18, -v14, v17, v16
	v_fmac_f32_e32 v17, v18, v15
	v_fma_f32 v14, -v14, v17, v16
	v_div_fmas_f32 v14, v14, v15, v17
	v_div_fixup_f32 v11, v14, v11, v13
	ds_write2st64_b32 v154, v10, v11 offset0:12 offset1:14
.LBB0_1006:
	s_or_b64 exec, exec, s[24:25]
	v_readfirstlane_b32 s24, v9
	v_cmp_gt_i32_e32 vcc, 16, v19
	v_lshl_add_u32 v13, v19, 2, v127
	v_subrev_f32_e32 v9, s24, v9
	v_mul_f32_e32 v9, 0x3fb8aa3b, v9
	v_exp_f32_e32 v9, v9
	s_and_b64 s[24:25], s[4:5], vcc
	v_add_u32_e32 v158, 64, v13
	v_xor_b32_e32 v184, v6, v7
	v_and_b32_e32 v184, 64, v184
	v_cmp_eq_u32_e32 vcc, 0, v184
	s_and_b64 s[72:73], vcc, s[24:25]
	s_andn2_b64 s[74:75], s[24:25], vcc
	v_mbcnt_lo_u32_b32 v184, s72, 0
	v_mbcnt_hi_u32_b32 v184, s73, v184
	v_mbcnt_lo_u32_b32 v185, s74, 0
	v_mbcnt_hi_u32_b32 v185, s75, v185
	v_add_u32_e32 v184, s77, v184
	v_sub_u32_e32 v185, s78, v185
	v_cndmask_b32_e32 v184, v185, v184, vcc
	v_lshl_add_u32 v158, v184, 2, v189
	s_bcnt1_i32_b64 s76, s[72:73]
	s_add_u32 s77, s77, s76
	s_bcnt1_i32_b64 s76, s[74:75]
	s_sub_u32 s78, s78, s76
	v_mov_b32_e32 v159, 0
	v_cndmask_b32_e64 v10, 0, v9, s[24:25]
	v_mov_b32_e32 v11, v10
	s_nop 1
	v_permlane32_swap_b32_e32 v10, v11
	v_add_f32_e32 v10, v10, v11
	v_mov_b32_e32 v11, v10
	s_nop 1
	v_permlane16_swap_b32_e32 v10, v11
	v_add_f32_e32 v10, v10, v11
	s_nop 1
	v_add_f32_dpp v10, v10, v10 row_ror:8 row_mask:0xf bank_mask:0xf bound_ctrl:1
	s_nop 1
	v_add_f32_dpp v10, v10, v10 row_ror:4 row_mask:0xf bank_mask:0xf bound_ctrl:1
	s_nop 1
	v_add_f32_dpp v10, v10, v10 quad_perm:[2,3,0,1] row_mask:0xf bank_mask:0xf bound_ctrl:1
	s_nop 1
	v_mov_b32_dpp v11, v10 quad_perm:[1,0,3,2] row_mask:0xf bank_mask:0xf bound_ctrl:1
	s_and_saveexec_b64 s[26:27], s[24:25]
	s_cbranch_execz .LBB0_1008
	v_lshlrev_b32_e32 v6, 7, v6
	v_and_b32_e32 v7, 0x7f, v7
	v_and_or_b32 v6, v6, s49, v7
	v_add_f32_e32 v7, v10, v11
	v_div_scale_f32 v10, s[28:29], v7, v7, v9
	v_rcp_f32_e32 v11, v10
	s_nop 0
	v_fma_f32 v13, -v10, v11, 1.0
	v_fmac_f32_e32 v11, v13, v11
	v_div_scale_f32 v13, vcc, v9, v7, v9
	v_mul_f32_e32 v14, v13, v11
	v_fma_f32 v15, -v10, v14, v13
	v_fmac_f32_e32 v14, v15, v11
	v_fma_f32 v10, -v10, v14, v13
	v_div_fmas_f32 v10, v10, v11, v14
	v_div_fixup_f32 v7, v10, v7, v9
	ds_write2st64_b32 v158, v6, v7 offset0:12 offset1:14
.LBB0_1008:
	s_or_b64 exec, exec, s[26:27]
	v_readfirstlane_b32 s26, v8
	v_cmp_gt_i32_e32 vcc, 16, v12
	v_lshl_add_u32 v9, v12, 2, v127
	v_subrev_f32_e32 v6, s26, v8
	v_mul_f32_e32 v6, 0x3fb8aa3b, v6
	v_exp_f32_e32 v6, v6
	s_and_b64 s[26:27], s[4:5], vcc
	v_mov_b32_e32 v161, 0
	v_add_u32_e32 v160, 0x80, v9
	v_xor_b32_e32 v184, v3, v4
	v_and_b32_e32 v184, 64, v184
	v_cmp_eq_u32_e32 vcc, 0, v184
	s_and_b64 s[72:73], vcc, s[26:27]
	s_andn2_b64 s[74:75], s[26:27], vcc
	v_mbcnt_lo_u32_b32 v184, s72, 0
	v_mbcnt_hi_u32_b32 v184, s73, v184
	v_mbcnt_lo_u32_b32 v185, s74, 0
	v_mbcnt_hi_u32_b32 v185, s75, v185
	v_add_u32_e32 v184, s77, v184
	v_sub_u32_e32 v185, s78, v185
	v_cndmask_b32_e32 v184, v185, v184, vcc
	v_lshl_add_u32 v160, v184, 2, v189
	s_bcnt1_i32_b64 s76, s[72:73]
	s_add_u32 s77, s77, s76
	s_bcnt1_i32_b64 s76, s[74:75]
	s_sub_u32 s78, s78, s76
	v_cndmask_b32_e64 v7, 0, v6, s[26:27]
	v_mov_b32_e32 v8, v7
	s_nop 1
	v_permlane32_swap_b32_e32 v7, v8
	v_add_f32_e32 v7, v7, v8
	v_mov_b32_e32 v8, v7
	s_nop 1
	v_permlane16_swap_b32_e32 v7, v8
	v_add_f32_e32 v7, v7, v8
	v_mov_b32_e32 v162, 0
	v_mov_b32_e32 v163, 0
	v_add_f32_dpp v7, v7, v7 row_ror:8 row_mask:0xf bank_mask:0xf bound_ctrl:1
	s_nop 1
	v_add_f32_dpp v7, v7, v7 row_ror:4 row_mask:0xf bank_mask:0xf bound_ctrl:1
	s_nop 1
	v_add_f32_dpp v7, v7, v7 quad_perm:[2,3,0,1] row_mask:0xf bank_mask:0xf bound_ctrl:1
	s_nop 1
	v_mov_b32_dpp v8, v7 quad_perm:[1,0,3,2] row_mask:0xf bank_mask:0xf bound_ctrl:1
	s_and_saveexec_b64 s[28:29], s[26:27]
	s_cbranch_execz .LBB0_1010
	v_lshlrev_b32_e32 v3, 7, v3
	v_and_b32_e32 v4, 0x7f, v4
	v_and_or_b32 v3, v3, s49, v4
	v_add_f32_e32 v4, v7, v8
	v_div_scale_f32 v7, s[42:43], v4, v4, v6
	v_rcp_f32_e32 v8, v7
	s_nop 0
	v_fma_f32 v9, -v7, v8, 1.0
	v_fmac_f32_e32 v8, v9, v8
	v_div_scale_f32 v9, vcc, v6, v4, v6
	v_mul_f32_e32 v10, v9, v8
	v_fma_f32 v11, -v7, v10, v9
	v_fmac_f32_e32 v10, v11, v8
	v_fma_f32 v7, -v7, v10, v9
	v_div_fmas_f32 v7, v7, v8, v10
	v_div_fixup_f32 v4, v7, v4, v6
	ds_write2st64_b32 v160, v3, v4 offset0:12 offset1:14
.LBB0_1010:
	s_or_b64 exec, exec, s[28:29]
	v_readfirstlane_b32 s28, v2
	v_cmp_gt_i32_e32 vcc, 16, v5
	v_lshl_add_u32 v5, v5, 2, v127
	v_subrev_f32_e32 v2, s28, v2
	v_mul_f32_e32 v2, 0x3fb8aa3b, v2
	v_exp_f32_e32 v2, v2
	s_and_b64 s[28:29], s[4:5], vcc
	v_add_u32_e32 v164, 0xc0, v5
	v_xor_b32_e32 v184, v0, v1
	v_and_b32_e32 v184, 64, v184
	v_cmp_eq_u32_e32 vcc, 0, v184
	s_and_b64 s[72:73], vcc, s[28:29]
	s_andn2_b64 s[74:75], s[28:29], vcc
	v_mbcnt_lo_u32_b32 v184, s72, 0
	v_mbcnt_hi_u32_b32 v184, s73, v184
	v_mbcnt_lo_u32_b32 v185, s74, 0
	v_mbcnt_hi_u32_b32 v185, s75, v185
	v_add_u32_e32 v184, s77, v184
	v_sub_u32_e32 v185, s78, v185
	v_cndmask_b32_e32 v184, v185, v184, vcc
	v_lshl_add_u32 v164, v184, 2, v189
	s_bcnt1_i32_b64 s76, s[72:73]
	s_add_u32 s77, s77, s76
	s_bcnt1_i32_b64 s76, s[74:75]
	s_sub_u32 s78, s78, s76
	v_mov_b32_e32 v165, 0
	v_cndmask_b32_e64 v3, 0, v2, s[28:29]
	v_mov_b32_e32 v4, v3
	s_nop 1
	v_permlane32_swap_b32_e32 v3, v4
	v_add_f32_e32 v3, v3, v4
	v_mov_b32_e32 v4, v3
	s_nop 1
	v_permlane16_swap_b32_e32 v3, v4
	v_add_f32_e32 v3, v3, v4
	s_nop 1
	v_add_f32_dpp v3, v3, v3 row_ror:8 row_mask:0xf bank_mask:0xf bound_ctrl:1
	s_nop 1
	v_add_f32_dpp v3, v3, v3 row_ror:4 row_mask:0xf bank_mask:0xf bound_ctrl:1
	s_nop 1
	v_add_f32_dpp v3, v3, v3 quad_perm:[2,3,0,1] row_mask:0xf bank_mask:0xf bound_ctrl:1
	s_nop 1
	v_mov_b32_dpp v4, v3 quad_perm:[1,0,3,2] row_mask:0xf bank_mask:0xf bound_ctrl:1
	s_and_saveexec_b64 s[42:43], s[28:29]
	s_cbranch_execz .LBB0_1012
	v_lshlrev_b32_e32 v0, 7, v0
	v_and_b32_e32 v1, 0x7f, v1
	v_and_or_b32 v0, v0, s49, v1
	v_add_f32_e32 v1, v3, v4
	v_div_scale_f32 v3, s[44:45], v1, v1, v2
	v_rcp_f32_e32 v4, v3
	s_nop 0
	v_fma_f32 v5, -v3, v4, 1.0
	v_fmac_f32_e32 v4, v5, v4
	v_div_scale_f32 v5, vcc, v2, v1, v2
	v_mul_f32_e32 v6, v5, v4
	v_fma_f32 v7, -v3, v6, v5
	v_fmac_f32_e32 v6, v7, v4
	v_fma_f32 v3, -v3, v6, v5
	v_div_fmas_f32 v3, v3, v4, v6
	v_div_fixup_f32 v1, v3, v1, v2
	ds_write2st64_b32 v164, v0, v1 offset0:12 offset1:14
.LBB0_1012:
	s_or_b64 exec, exec, s[42:43]
	s_branch .Lg1_tok_next
.Lg1_rtok:
	s_waitcnt vmcnt(0)
	s_cmp_lg_u32 s96, 1
	s_cbranch_scc1 .Lg1_noscale
	ds_read_b64 v[228:229], v226 offset:3072
	s_waitcnt lgkmcnt(0)
	v_lshlrev_b32_e32 v228, 2, v228
	v_lshlrev_b32_e32 v229, 2, v229
	global_load_dword v230, v228, s[36:37]
	global_load_dword v231, v229, s[36:37]
	global_load_dword v232, v228, s[38:39]
	global_load_dword v233, v229, s[38:39]
.Lg1_noscale:
	s_mov_b32 s63, s32
	v_add_u32_e32 v183, s97, v134
	v_lshlrev_b32_e32 v16, 16, v208
	v_and_b32_e32 v208, 0xffff0000, v208
	v_lshlrev_b32_e32 v17, 16, v209
	v_and_b32_e32 v209, 0xffff0000, v209
	v_lshlrev_b32_e32 v18, 16, v210
	v_and_b32_e32 v210, 0xffff0000, v210
	v_lshlrev_b32_e32 v19, 16, v211
	v_and_b32_e32 v211, 0xffff0000, v211
	v_lshlrev_b32_e32 v20, 16, v212
	v_and_b32_e32 v212, 0xffff0000, v212
	v_lshlrev_b32_e32 v21, 16, v213
	v_and_b32_e32 v213, 0xffff0000, v213
	v_lshlrev_b32_e32 v22, 16, v214
	v_and_b32_e32 v214, 0xffff0000, v214
	v_lshlrev_b32_e32 v23, 16, v215
	v_and_b32_e32 v215, 0xffff0000, v215
	v_lshlrev_b32_e32 v24, 16, v216
	v_and_b32_e32 v216, 0xffff0000, v216
	v_lshlrev_b32_e32 v25, 16, v217
	v_and_b32_e32 v217, 0xffff0000, v217
	v_lshlrev_b32_e32 v26, 16, v218
	v_and_b32_e32 v218, 0xffff0000, v218
	v_lshlrev_b32_e32 v27, 16, v219
	v_and_b32_e32 v219, 0xffff0000, v219
	v_lshlrev_b32_e32 v28, 16, v220
	v_and_b32_e32 v220, 0xffff0000, v220
	v_lshlrev_b32_e32 v29, 16, v221
	v_and_b32_e32 v221, 0xffff0000, v221
	v_lshlrev_b32_e32 v30, 16, v222
	v_and_b32_e32 v222, 0xffff0000, v222
	v_lshlrev_b32_e32 v31, 16, v223
	v_and_b32_e32 v223, 0xffff0000, v223
	v_cvt_pk_f16_f32 v166, v16, v208
	v_cvt_pk_f16_f32 v167, v17, v209
	v_cvt_pk_f16_f32 v168, v18, v210
	v_cvt_pk_f16_f32 v169, v19, v211
	v_cvt_pk_f16_f32 v170, v20, v212
	v_cvt_pk_f16_f32 v171, v21, v213
	v_cvt_pk_f16_f32 v172, v22, v214
	v_cvt_pk_f16_f32 v173, v23, v215
	v_cvt_pk_f16_f32 v174, v24, v216
	v_cvt_pk_f16_f32 v175, v25, v217
	v_cvt_pk_f16_f32 v177, v26, v218
	v_cvt_pk_f16_f32 v178, v27, v219
	v_cvt_pk_f16_f32 v179, v28, v220
	v_cvt_pk_f16_f32 v180, v29, v221
	v_cvt_pk_f16_f32 v181, v30, v222
	v_cvt_pk_f16_f32 v182, v31, v223
	v_ashrrev_i32_e32 v225, 31, v227
	v_mov_b32_e32 v224, v227
	v_lshlrev_b64 v[224:225], 11, v[224:225]
	v_lshl_add_u64 v[224:225], v[120:121], 0, v[224:225]
	global_load_dwordx2 v[208:209], v[224:225], off
	global_load_dwordx2 v[210:211], v[224:225], off offset:256
	global_load_dwordx2 v[212:213], v[224:225], off offset:512
	global_load_dwordx2 v[214:215], v[224:225], off offset:768
	global_load_dwordx2 v[216:217], v[224:225], off offset:1024
	global_load_dwordx2 v[218:219], v[224:225], off offset:1280
	global_load_dwordx2 v[220:221], v[224:225], off offset:1536
	global_load_dwordx2 v[222:223], v[224:225], off offset:1792
	s_cmp_lg_u32 s96, 1
	s_cbranch_scc1 .Lg1_noscale2
	s_waitcnt vmcnt(8)
	ds_write_b64 v226, v[230:231] offset:4608
	ds_write_b64 v226, v[232:233] offset:5120
.Lg1_noscale2:
	s_waitcnt lgkmcnt(0)
	s_setprio 1
	s_branch .LBB0_1015

.LBB0_1014:
	s_or_b64 exec, exec, s[42:43]
	s_add_i32 s63, s63, 32
	s_cmp_gt_u32 s63, s71
	v_add_u32_e32 v183, 0x80, v183
	s_cbranch_scc1 .LBB0_977
.LBB0_1015:
	ds_read_b128 v[0:3], v183
	ds_read_b128 v[4:7], v183 offset:16
	ds_read_b128 v[8:11], v183 offset:32
	ds_read_b128 v[12:15], v183 offset:48
	s_cmpk_eq_i32 s63, 0xffe0
	s_waitcnt lgkmcnt(3)
	v_mul_lo_u32 v0, v0, s51
	v_add_u32_e32 v16, v0, v128
	v_add_u32_e32 v0, v0, v136
	global_load_dwordx4 v[106:109], v16, s[40:41]
	global_load_dwordx2 v[110:111], v0, s[40:41]
	v_mul_lo_u32 v0, v1, s51
	v_add_u32_e32 v1, v0, v128
	v_add_u32_e32 v0, v0, v136
	global_load_dwordx4 v[100:103], v1, s[40:41]
	global_load_dwordx2 v[104:105], v0, s[40:41]
	v_mul_lo_u32 v0, v2, s51
	v_add_u32_e32 v1, v0, v128
	v_add_u32_e32 v0, v0, v136
	global_load_dwordx4 v[94:97], v1, s[40:41]
	global_load_dwordx2 v[98:99], v0, s[40:41]
	v_mul_lo_u32 v0, v3, s51
	v_add_u32_e32 v1, v0, v128
	v_add_u32_e32 v0, v0, v136
	global_load_dwordx4 v[88:91], v1, s[40:41]
	global_load_dwordx2 v[92:93], v0, s[40:41]
	s_waitcnt lgkmcnt(2)
	v_mul_lo_u32 v0, v4, s51
	v_add_u32_e32 v1, v0, v128
	v_add_u32_e32 v0, v0, v136
	global_load_dwordx4 v[82:85], v1, s[40:41]
	global_load_dwordx2 v[86:87], v0, s[40:41]
	v_mul_lo_u32 v0, v5, s51
	v_add_u32_e32 v1, v0, v128
	v_add_u32_e32 v0, v0, v136
	global_load_dwordx4 v[76:79], v1, s[40:41]
	global_load_dwordx2 v[80:81], v0, s[40:41]
	v_mul_lo_u32 v0, v6, s51
	v_add_u32_e32 v1, v0, v128
	v_add_u32_e32 v0, v0, v136
	global_load_dwordx4 v[70:73], v1, s[40:41]
	global_load_dwordx2 v[74:75], v0, s[40:41]
	v_mul_lo_u32 v0, v7, s51
	v_add_u32_e32 v1, v0, v128
	v_add_u32_e32 v0, v0, v136
	global_load_dwordx4 v[64:67], v1, s[40:41]
	global_load_dwordx2 v[68:69], v0, s[40:41]
	s_waitcnt lgkmcnt(1)
	v_mul_lo_u32 v0, v8, s51
	v_add_u32_e32 v1, v0, v128
	v_add_u32_e32 v0, v0, v136
	global_load_dwordx4 v[58:61], v1, s[40:41]
	global_load_dwordx2 v[62:63], v0, s[40:41]
	v_mul_lo_u32 v0, v9, s51
	v_add_u32_e32 v1, v0, v128
	v_add_u32_e32 v0, v0, v136
	global_load_dwordx4 v[52:55], v1, s[40:41]
	global_load_dwordx2 v[56:57], v0, s[40:41]
	v_mul_lo_u32 v0, v10, s51
	v_add_u32_e32 v1, v0, v128
	v_add_u32_e32 v0, v0, v136
	global_load_dwordx4 v[46:49], v1, s[40:41]
	global_load_dwordx2 v[50:51], v0, s[40:41]
	v_mul_lo_u32 v0, v11, s51
	v_add_u32_e32 v1, v0, v128
	v_add_u32_e32 v0, v0, v136
	global_load_dwordx4 v[40:43], v1, s[40:41]
	global_load_dwordx2 v[44:45], v0, s[40:41]
	s_waitcnt lgkmcnt(0)
	v_mul_lo_u32 v0, v12, s51
	v_add_u32_e32 v1, v0, v128
	v_add_u32_e32 v0, v0, v136
	global_load_dwordx4 v[34:37], v1, s[40:41]
	global_load_dwordx2 v[38:39], v0, s[40:41]
	v_mul_lo_u32 v0, v13, s51
	v_add_u32_e32 v1, v0, v128
	v_add_u32_e32 v0, v0, v136
	global_load_dwordx4 v[28:31], v1, s[40:41]
	global_load_dwordx2 v[32:33], v0, s[40:41]
	v_mul_lo_u32 v0, v14, s51
	v_add_u32_e32 v1, v0, v128
	v_add_u32_e32 v0, v0, v136
	global_load_dwordx4 v[22:25], v1, s[40:41]
	global_load_dwordx2 v[26:27], v0, s[40:41]
	v_mul_lo_u32 v0, v15, s51
	v_add_u32_e32 v1, v0, v128
	v_add_u32_e32 v0, v0, v136
	global_load_dwordx4 v[16:19], v1, s[40:41]
	global_load_dwordx2 v[20:21], v0, s[40:41]
	s_branch .LBB0_1026
	s_and_saveexec_b64 s[42:43], s[14:15]
	s_cbranch_execnz .LBB0_1031
	s_or_b64 exec, exec, s[42:43]
	s_and_saveexec_b64 s[42:43], s[16:17]
	s_cbranch_execnz .LBB0_1032
